# gemm_up K-loop: K-tile kt+2 LDS-DMA issued mid-iteration after 2nd barrier (1.5-iter prefetch), counted lgkmcnt; on top of gemm160 3-stage ring
# speedup vs baseline: 1.0161x; 1.0161x over previous
.LBB0_830:
	s_mul_hi_i32 s42, s48, 0x2e8ba2e9
	s_lshr_b32 s43, s42, 31
	s_ashr_i32 s42, s42, 5
	s_add_i32 s42, s42, s43
	s_lshl_b32 s42, s42, 3
	s_and_b32 s43, s48, 7
	s_or_b32 s62, s42, s43
	s_ashr_i32 s42, s48, 3
	s_mul_hi_i32 s43, s42, 0x2e8ba2e9
	s_lshr_b32 s48, s43, 31
	s_ashr_i32 s43, s43, 2
	s_add_i32 s43, s43, s48
	s_mul_i32 s43, s43, 22
	s_sub_i32 s58, s42, s43
	s_ashr_i32 s63, s62, 31
	s_ashr_i32 s59, s58, 31
	s_lshl_b64 s[42:43], s[62:63], 19
	s_lshl_b64 s[48:49], s[58:59], 19
	v_readfirstlane_b32 s59, v178
	v_add_u32_e32 v4, 0x8000, v178
	v_lshl_add_u64 v[0:1], v[132:133], 0, s[42:43]
	s_mov_b32 m0, s59
	v_readfirstlane_b32 s59, v4
	v_add_u32_e32 v6, 0x2000, v178
	v_lshl_add_u64 v[2:3], v[134:135], 0, s[48:49]
	global_load_lds_dwordx4 v[0:1], off
	s_mov_b32 m0, s59
	s_mov_b64 s[96:97], 0x20000
	v_readfirstlane_b32 s59, v6
	v_add_u32_e32 v6, 0xa000, v178
	global_load_lds_dwordx4 v[2:3], off
	v_lshl_add_u64 v[4:5], v[0:1], 0, s[96:97]
	s_mov_b32 m0, s59
	v_readfirstlane_b32 s59, v6
	v_add_u32_e32 v6, 0x4000, v178
	global_load_lds_dwordx4 v[4:5], off
	v_lshl_add_u64 v[4:5], v[2:3], 0, s[96:97]
	s_mov_b32 m0, s59
	v_readfirstlane_b32 s59, v6
	v_add_u32_e32 v6, 0xc000, v178
	global_load_lds_dwordx4 v[4:5], off
	v_lshl_add_u64 v[4:5], v[0:1], 0, s[74:75]
	s_mov_b32 m0, s59
	v_readfirstlane_b32 s59, v6
	global_load_lds_dwordx4 v[4:5], off
	v_lshl_add_u64 v[4:5], v[2:3], 0, s[74:75]
	s_mov_b32 m0, s59
	s_mov_b64 s[96:97], 0x60000
	global_load_lds_dwordx4 v[4:5], off
	v_add_u32_e32 v4, 0x6000, v178
	v_lshl_add_u64 v[0:1], v[0:1], 0, s[96:97]
	v_readfirstlane_b32 s59, v4
	s_mov_b32 m0, s59
	s_mov_b64 s[72:73], 0x20000
	global_load_lds_dwordx4 v[0:1], off
	v_lshl_add_u64 v[0:1], v[2:3], 0, s[96:97]
	v_add_u32_e32 v2, 0xe000, v178
	v_lshl_add_u64 v[174:175], v[170:171], 0, s[48:49]
	v_readfirstlane_b32 s59, v2
	s_mov_b32 m0, s59
	v_lshl_add_u64 v[176:177], v[172:173], 0, s[42:43]
	global_load_lds_dwordx4 v[0:1], off
	v_mov_b32_e32 v0, 0
	s_mov_b32 s42, 0
	s_mov_b64 s[96:97], 0
	v_mov_b32_e32 v1, v0
	v_mov_b32_e32 v2, v0
	v_mov_b32_e32 v3, v0
	v_mov_b32_e32 v4, v0
	v_mov_b32_e32 v5, v0
	v_mov_b32_e32 v6, v0
	v_mov_b32_e32 v7, v0
	v_mov_b32_e32 v8, v0
	v_mov_b32_e32 v9, v0
	v_mov_b32_e32 v10, v0
	v_mov_b32_e32 v11, v0
	v_mov_b32_e32 v12, v0
	v_mov_b32_e32 v13, v0
	v_mov_b32_e32 v14, v0
	v_mov_b32_e32 v15, v0
	v_mov_b32_e32 v16, v0
	v_mov_b32_e32 v17, v0
	v_mov_b32_e32 v18, v0
	v_mov_b32_e32 v19, v0
	v_mov_b32_e32 v20, v0
	v_mov_b32_e32 v21, v0
	v_mov_b32_e32 v22, v0
	v_mov_b32_e32 v23, v0
	v_mov_b32_e32 v24, v0
	v_mov_b32_e32 v25, v0
	v_mov_b32_e32 v26, v0
	v_mov_b32_e32 v27, v0
	v_mov_b32_e32 v28, v0
	v_mov_b32_e32 v29, v0
	v_mov_b32_e32 v30, v0
	v_mov_b32_e32 v31, v0
	v_mov_b32_e32 v32, v0
	v_mov_b32_e32 v33, v0
	v_mov_b32_e32 v34, v0
	v_mov_b32_e32 v35, v0
	v_mov_b32_e32 v36, v0
	v_mov_b32_e32 v37, v0
	v_mov_b32_e32 v38, v0
	v_mov_b32_e32 v39, v0
	v_mov_b32_e32 v40, v0
	v_mov_b32_e32 v41, v0
	v_mov_b32_e32 v42, v0
	v_mov_b32_e32 v43, v0
	v_mov_b32_e32 v44, v0
	v_mov_b32_e32 v45, v0
	v_mov_b32_e32 v46, v0
	v_mov_b32_e32 v47, v0
	v_mov_b32_e32 v48, v0
	v_mov_b32_e32 v49, v0
	v_mov_b32_e32 v50, v0
	v_mov_b32_e32 v51, v0
	v_mov_b32_e32 v52, v0
	v_mov_b32_e32 v53, v0
	v_mov_b32_e32 v54, v0
	v_mov_b32_e32 v55, v0
	v_mov_b32_e32 v56, v0
	v_mov_b32_e32 v57, v0
	v_mov_b32_e32 v58, v0
	v_mov_b32_e32 v59, v0
	v_mov_b32_e32 v60, v0
	v_mov_b32_e32 v61, v0
	v_mov_b32_e32 v62, v0
	v_mov_b32_e32 v63, v0
	v_mov_b32_e32 v64, v0
	v_mov_b32_e32 v65, v0
	v_mov_b32_e32 v66, v0
	v_mov_b32_e32 v67, v0
	v_mov_b32_e32 v68, v0
	v_mov_b32_e32 v69, v0
	v_mov_b32_e32 v70, v0
	v_mov_b32_e32 v71, v0
	v_mov_b32_e32 v72, v0
	v_mov_b32_e32 v73, v0
	v_mov_b32_e32 v74, v0
	v_mov_b32_e32 v75, v0
	v_mov_b32_e32 v76, v0
	v_mov_b32_e32 v77, v0
	v_mov_b32_e32 v78, v0
	v_mov_b32_e32 v79, v0
	v_mov_b32_e32 v80, v0
	v_mov_b32_e32 v81, v0
	v_mov_b32_e32 v82, v0
	v_mov_b32_e32 v83, v0
	v_mov_b32_e32 v84, v0
	v_mov_b32_e32 v85, v0
	v_mov_b32_e32 v86, v0
	v_mov_b32_e32 v87, v0
	v_mov_b32_e32 v88, v0
	v_mov_b32_e32 v89, v0
	v_mov_b32_e32 v90, v0
	v_mov_b32_e32 v91, v0
	v_mov_b32_e32 v92, v0
	v_mov_b32_e32 v93, v0
	v_mov_b32_e32 v94, v0
	v_mov_b32_e32 v95, v0
	v_mov_b32_e32 v96, v0
	v_mov_b32_e32 v97, v0
	v_mov_b32_e32 v98, v0
	v_mov_b32_e32 v99, v0
	v_mov_b32_e32 v100, v0
	v_mov_b32_e32 v101, v0
	v_mov_b32_e32 v102, v0
	v_mov_b32_e32 v103, v0
	v_mov_b32_e32 v104, v0
	v_mov_b32_e32 v105, v0
	v_mov_b32_e32 v106, v0
	v_mov_b32_e32 v107, v0
	v_mov_b32_e32 v108, v0
	v_mov_b32_e32 v109, v0
	v_mov_b32_e32 v110, v0
	v_mov_b32_e32 v111, v0
	v_mov_b32_e32 v112, v0
	v_mov_b32_e32 v113, v0
	v_mov_b32_e32 v114, v0
	v_mov_b32_e32 v115, v0
	v_mov_b32_e32 v116, v0
	v_mov_b32_e32 v117, v0
	v_mov_b32_e32 v118, v0
	v_mov_b32_e32 v119, v0
	v_mov_b32_e32 v120, v0
	v_mov_b32_e32 v121, v0
	v_mov_b32_e32 v122, v0
	v_mov_b32_e32 v123, v0
	v_mov_b32_e32 v124, v0
	v_mov_b32_e32 v125, v0
	v_mov_b32_e32 v126, v0
	v_mov_b32_e32 v127, v0
	v_add_u32_e32 v229, 0x10000, v178
	s_nop 0
	v_readfirstlane_b32 s98, v229
	s_nop 3
	s_add_u32 s48, s96, s78
	s_addc_u32 s49, s97, s79
	v_lshl_add_u64 v[220:221], v[176:177], 0, s[48:49]
	s_mov_b32 m0, s98
	s_nop 0
	global_load_lds_dwordx4 v[220:221], off
	s_add_u32 s48, s96, 0x560080
	s_addc_u32 s49, s97, 0
	v_lshl_add_u64 v[220:221], v[174:175], 0, s[48:49]
	s_add_u32 m0, s98, 0x8000
	s_nop 0
	global_load_lds_dwordx4 v[220:221], off
	s_add_u32 s48, s96, s80
	s_addc_u32 s49, s97, s81
	v_lshl_add_u64 v[220:221], v[176:177], 0, s[48:49]
	s_add_u32 m0, s98, 0x2000
	s_nop 0
	global_load_lds_dwordx4 v[220:221], off
	s_add_u32 s48, s96, 0x580080
	s_addc_u32 s49, s97, 0
	v_lshl_add_u64 v[220:221], v[174:175], 0, s[48:49]
	s_add_u32 m0, s98, 0xa000
	s_nop 0
	global_load_lds_dwordx4 v[220:221], off
	s_add_u32 s48, s96, s82
	s_addc_u32 s49, s97, s83
	v_lshl_add_u64 v[220:221], v[176:177], 0, s[48:49]
	s_add_u32 m0, s98, 0x4000
	s_nop 0
	global_load_lds_dwordx4 v[220:221], off
	s_add_u32 s48, s96, 0x5a0080
	s_addc_u32 s49, s97, 0
	v_lshl_add_u64 v[220:221], v[174:175], 0, s[48:49]
	s_add_u32 m0, s98, 0xc000
	s_nop 0
	global_load_lds_dwordx4 v[220:221], off
	s_add_u32 s48, s96, 0x2c91080
	s_addc_u32 s49, s97, 0
	v_lshl_add_u64 v[220:221], v[176:177], 0, s[48:49]
	s_add_u32 m0, s98, 0x6000
	s_nop 0
	global_load_lds_dwordx4 v[220:221], off
	s_add_u32 s48, s96, 0x5c0080
	s_addc_u32 s49, s97, 0
	v_lshl_add_u64 v[220:221], v[174:175], 0, s[48:49]
	s_add_u32 m0, s98, 0xe000
	s_nop 0
	global_load_lds_dwordx4 v[220:221], off
.LBB0_831:
	s_and_b32 s43, s42, 0x10000
	v_add_u32_e32 v229, s43, v178
	s_add_u32 s100, s96, 0x80
	s_addc_u32 s101, s97, 0
	v_add_u32_e32 v195, s43, v179
	v_add_u32_e32 v220, s43, v131
	v_readfirstlane_b32 s98, v229
	v_add_u32_e32 v208, v195, v180
	v_add_u32_e32 v221, v220, v180
	s_waitcnt vmcnt(8) lgkmcnt(0)
	s_barrier
	ds_read_b128 v[196:199], v208 offset:32768
	ds_read_b128 v[200:203], v208 offset:34816
	ds_read_b128 v[204:207], v208 offset:36864
	ds_read_b128 v[208:211], v208 offset:38912
	ds_read_b128 v[212:215], v221
	ds_read_b128 v[216:219], v221 offset:2048
	ds_read_b128 v[230:233], v221 offset:4096
	ds_read_b128 v[234:237], v221 offset:6144
	ds_read_b128 v[238:241], v221 offset:8192
	ds_read_b128 v[242:245], v221 offset:10240
	ds_read_b128 v[246:249], v221 offset:12288
	ds_read_b128 v[250:253], v221 offset:14336
	s_waitcnt lgkmcnt(7)
	v_mfma_f32_16x16x32_bf16 v[124:127], v[196:199], v[212:215], v[124:127]
	v_mfma_f32_16x16x32_bf16 v[120:123], v[200:203], v[212:215], v[120:123]
	v_mfma_f32_16x16x32_bf16 v[116:119], v[204:207], v[212:215], v[116:119]
	v_mfma_f32_16x16x32_bf16 v[112:115], v[208:211], v[212:215], v[112:115]
	s_waitcnt lgkmcnt(6)
	v_mfma_f32_16x16x32_bf16 v[108:111], v[196:199], v[216:219], v[108:111]
	v_mfma_f32_16x16x32_bf16 v[104:107], v[200:203], v[216:219], v[104:107]
	v_mfma_f32_16x16x32_bf16 v[100:103], v[204:207], v[216:219], v[100:103]
	v_mfma_f32_16x16x32_bf16 v[96:99], v[208:211], v[216:219], v[96:99]
	s_waitcnt lgkmcnt(5)
	v_mfma_f32_16x16x32_bf16 v[92:95], v[196:199], v[230:233], v[92:95]
	v_mfma_f32_16x16x32_bf16 v[88:91], v[200:203], v[230:233], v[88:91]
	v_mfma_f32_16x16x32_bf16 v[84:87], v[204:207], v[230:233], v[84:87]
	v_mfma_f32_16x16x32_bf16 v[80:83], v[208:211], v[230:233], v[80:83]
	s_waitcnt lgkmcnt(4)
	v_mfma_f32_16x16x32_bf16 v[76:79], v[196:199], v[234:237], v[76:79]
	v_mfma_f32_16x16x32_bf16 v[72:75], v[200:203], v[234:237], v[72:75]
	v_mfma_f32_16x16x32_bf16 v[68:71], v[204:207], v[234:237], v[68:71]
	v_mfma_f32_16x16x32_bf16 v[64:67], v[208:211], v[234:237], v[64:67]
	v_add_u32_e32 v220, v220, v181
	ds_read_b128 v[212:215], v220
	ds_read_b128 v[216:219], v220 offset:2048
	ds_read_b128 v[230:233], v220 offset:4096
	ds_read_b128 v[234:237], v220 offset:6144
	s_waitcnt lgkmcnt(7)
	v_mfma_f32_16x16x32_bf16 v[60:63], v[196:199], v[238:241], v[60:63]
	v_mfma_f32_16x16x32_bf16 v[56:59], v[200:203], v[238:241], v[56:59]
	v_mfma_f32_16x16x32_bf16 v[52:55], v[204:207], v[238:241], v[52:55]
	v_mfma_f32_16x16x32_bf16 v[48:51], v[208:211], v[238:241], v[48:51]
	s_waitcnt lgkmcnt(6)
	v_mfma_f32_16x16x32_bf16 v[44:47], v[196:199], v[242:245], v[44:47]
	v_mfma_f32_16x16x32_bf16 v[40:43], v[200:203], v[242:245], v[40:43]
	v_mfma_f32_16x16x32_bf16 v[36:39], v[204:207], v[242:245], v[36:39]
	v_mfma_f32_16x16x32_bf16 v[32:35], v[208:211], v[242:245], v[32:35]
	s_waitcnt lgkmcnt(5)
	v_mfma_f32_16x16x32_bf16 v[28:31], v[196:199], v[246:249], v[28:31]
	v_mfma_f32_16x16x32_bf16 v[24:27], v[200:203], v[246:249], v[24:27]
	v_mfma_f32_16x16x32_bf16 v[20:23], v[204:207], v[246:249], v[20:23]
	v_mfma_f32_16x16x32_bf16 v[16:19], v[208:211], v[246:249], v[16:19]
	s_waitcnt lgkmcnt(4)
	v_mfma_f32_16x16x32_bf16 v[12:15], v[196:199], v[250:253], v[12:15]
	v_mfma_f32_16x16x32_bf16 v[8:11], v[200:203], v[250:253], v[8:11]
	v_mfma_f32_16x16x32_bf16 v[4:7], v[204:207], v[250:253], v[4:7]
	v_mfma_f32_16x16x32_bf16 v[0:3], v[208:211], v[250:253], v[0:3]
	v_add_u32_e32 v195, v195, v181
	ds_read_b128 v[196:199], v195 offset:32768
	ds_read_b128 v[200:203], v195 offset:34816
	ds_read_b128 v[204:207], v195 offset:36864
	ds_read_b128 v[208:211], v195 offset:38912
	ds_read_b128 v[238:241], v220 offset:8192
	ds_read_b128 v[242:245], v220 offset:10240
	ds_read_b128 v[246:249], v220 offset:12288
	ds_read_b128 v[250:253], v220 offset:14336
	s_add_u32 s48, s100, s78
	s_addc_u32 s49, s101, s79
	v_lshl_add_u64 v[220:221], v[176:177], 0, s[48:49]
	s_mov_b32 m0, s98
	s_waitcnt lgkmcnt(0)
	s_barrier
	global_load_lds_dwordx4 v[220:221], off
	s_add_u32 s48, s100, 0x560080
	s_addc_u32 s49, s101, 0
	v_lshl_add_u64 v[220:221], v[174:175], 0, s[48:49]
	s_add_u32 m0, s98, 0x8000
	v_mfma_f32_16x16x32_bf16 v[124:127], v[196:199], v[212:215], v[124:127]
	v_mfma_f32_16x16x32_bf16 v[120:123], v[200:203], v[212:215], v[120:123]
	v_mfma_f32_16x16x32_bf16 v[116:119], v[204:207], v[212:215], v[116:119]
	v_mfma_f32_16x16x32_bf16 v[112:115], v[208:211], v[212:215], v[112:115]
	global_load_lds_dwordx4 v[220:221], off
	s_add_u32 s48, s100, s80
	s_addc_u32 s49, s101, s81
	v_lshl_add_u64 v[220:221], v[176:177], 0, s[48:49]
	s_add_u32 m0, s98, 0x2000
	v_mfma_f32_16x16x32_bf16 v[108:111], v[196:199], v[216:219], v[108:111]
	v_mfma_f32_16x16x32_bf16 v[104:107], v[200:203], v[216:219], v[104:107]
	v_mfma_f32_16x16x32_bf16 v[100:103], v[204:207], v[216:219], v[100:103]
	v_mfma_f32_16x16x32_bf16 v[96:99], v[208:211], v[216:219], v[96:99]
	global_load_lds_dwordx4 v[220:221], off
	s_add_u32 s48, s100, 0x580080
	s_addc_u32 s49, s101, 0
	v_lshl_add_u64 v[220:221], v[174:175], 0, s[48:49]
	s_add_u32 m0, s98, 0xa000
	v_mfma_f32_16x16x32_bf16 v[92:95], v[196:199], v[230:233], v[92:95]
	v_mfma_f32_16x16x32_bf16 v[88:91], v[200:203], v[230:233], v[88:91]
	v_mfma_f32_16x16x32_bf16 v[84:87], v[204:207], v[230:233], v[84:87]
	v_mfma_f32_16x16x32_bf16 v[80:83], v[208:211], v[230:233], v[80:83]
	global_load_lds_dwordx4 v[220:221], off
	s_add_u32 s48, s100, s82
	s_addc_u32 s49, s101, s83
	v_lshl_add_u64 v[220:221], v[176:177], 0, s[48:49]
	s_add_u32 m0, s98, 0x4000
	v_mfma_f32_16x16x32_bf16 v[76:79], v[196:199], v[234:237], v[76:79]
	v_mfma_f32_16x16x32_bf16 v[72:75], v[200:203], v[234:237], v[72:75]
	v_mfma_f32_16x16x32_bf16 v[68:71], v[204:207], v[234:237], v[68:71]
	v_mfma_f32_16x16x32_bf16 v[64:67], v[208:211], v[234:237], v[64:67]
	global_load_lds_dwordx4 v[220:221], off
	s_add_u32 s48, s100, 0x5a0080
	s_addc_u32 s49, s101, 0
	v_lshl_add_u64 v[220:221], v[174:175], 0, s[48:49]
	s_add_u32 m0, s98, 0xc000
	v_mfma_f32_16x16x32_bf16 v[60:63], v[196:199], v[238:241], v[60:63]
	v_mfma_f32_16x16x32_bf16 v[56:59], v[200:203], v[238:241], v[56:59]
	v_mfma_f32_16x16x32_bf16 v[52:55], v[204:207], v[238:241], v[52:55]
	v_mfma_f32_16x16x32_bf16 v[48:51], v[208:211], v[238:241], v[48:51]
	global_load_lds_dwordx4 v[220:221], off
	s_add_u32 s48, s100, 0x2c91080
	s_addc_u32 s49, s101, 0
	v_lshl_add_u64 v[220:221], v[176:177], 0, s[48:49]
	s_add_u32 m0, s98, 0x6000
	v_mfma_f32_16x16x32_bf16 v[44:47], v[196:199], v[242:245], v[44:47]
	v_mfma_f32_16x16x32_bf16 v[40:43], v[200:203], v[242:245], v[40:43]
	v_mfma_f32_16x16x32_bf16 v[36:39], v[204:207], v[242:245], v[36:39]
	v_mfma_f32_16x16x32_bf16 v[32:35], v[208:211], v[242:245], v[32:35]
	global_load_lds_dwordx4 v[220:221], off
	s_add_u32 s48, s100, 0x5c0080
	s_addc_u32 s49, s101, 0
	v_lshl_add_u64 v[220:221], v[174:175], 0, s[48:49]
	s_add_u32 m0, s98, 0xe000
	v_mfma_f32_16x16x32_bf16 v[28:31], v[196:199], v[246:249], v[28:31]
	v_mfma_f32_16x16x32_bf16 v[24:27], v[200:203], v[246:249], v[24:27]
	v_mfma_f32_16x16x32_bf16 v[20:23], v[204:207], v[246:249], v[20:23]
	v_mfma_f32_16x16x32_bf16 v[16:19], v[208:211], v[246:249], v[16:19]
	global_load_lds_dwordx4 v[220:221], off
	v_mfma_f32_16x16x32_bf16 v[12:15], v[196:199], v[250:253], v[12:15]
	v_mfma_f32_16x16x32_bf16 v[8:11], v[200:203], v[250:253], v[8:11]
	v_mfma_f32_16x16x32_bf16 v[4:7], v[204:207], v[250:253], v[4:7]
	v_mfma_f32_16x16x32_bf16 v[0:3], v[208:211], v[250:253], v[0:3]
	s_add_i32 s42, s42, 0x10000
	s_add_u32 s96, s96, 0x80
	s_addc_u32 s97, s97, 0
	s_cmpk_lg_i32 s96, 0x700
	s_cbranch_scc1 .LBB0_831
	s_and_b32 s43, s42, 0x10000
	v_add_u32_e32 v195, s43, v179
	v_add_u32_e32 v220, s43, v131
	v_add_u32_e32 v208, v195, v180
	v_add_u32_e32 v221, v220, v180
	s_waitcnt vmcnt(8) lgkmcnt(0)
	s_barrier
	ds_read_b128 v[196:199], v208 offset:32768
	ds_read_b128 v[200:203], v208 offset:34816
	ds_read_b128 v[204:207], v208 offset:36864
	ds_read_b128 v[208:211], v208 offset:38912
	ds_read_b128 v[212:215], v221
	ds_read_b128 v[216:219], v221 offset:2048
	ds_read_b128 v[230:233], v221 offset:4096
	ds_read_b128 v[234:237], v221 offset:6144
	ds_read_b128 v[238:241], v221 offset:8192
	ds_read_b128 v[242:245], v221 offset:10240
	ds_read_b128 v[246:249], v221 offset:12288
	ds_read_b128 v[250:253], v221 offset:14336
	s_waitcnt lgkmcnt(7)
	v_mfma_f32_16x16x32_bf16 v[124:127], v[196:199], v[212:215], v[124:127]
	v_mfma_f32_16x16x32_bf16 v[120:123], v[200:203], v[212:215], v[120:123]
	v_mfma_f32_16x16x32_bf16 v[116:119], v[204:207], v[212:215], v[116:119]
	v_mfma_f32_16x16x32_bf16 v[112:115], v[208:211], v[212:215], v[112:115]
	s_waitcnt lgkmcnt(6)
	v_mfma_f32_16x16x32_bf16 v[108:111], v[196:199], v[216:219], v[108:111]
	v_mfma_f32_16x16x32_bf16 v[104:107], v[200:203], v[216:219], v[104:107]
	v_mfma_f32_16x16x32_bf16 v[100:103], v[204:207], v[216:219], v[100:103]
	v_mfma_f32_16x16x32_bf16 v[96:99], v[208:211], v[216:219], v[96:99]
	s_waitcnt lgkmcnt(5)
	v_mfma_f32_16x16x32_bf16 v[92:95], v[196:199], v[230:233], v[92:95]
	v_mfma_f32_16x16x32_bf16 v[88:91], v[200:203], v[230:233], v[88:91]
	v_mfma_f32_16x16x32_bf16 v[84:87], v[204:207], v[230:233], v[84:87]
	v_mfma_f32_16x16x32_bf16 v[80:83], v[208:211], v[230:233], v[80:83]
	s_waitcnt lgkmcnt(4)
	v_mfma_f32_16x16x32_bf16 v[76:79], v[196:199], v[234:237], v[76:79]
	v_mfma_f32_16x16x32_bf16 v[72:75], v[200:203], v[234:237], v[72:75]
	v_mfma_f32_16x16x32_bf16 v[68:71], v[204:207], v[234:237], v[68:71]
	v_mfma_f32_16x16x32_bf16 v[64:67], v[208:211], v[234:237], v[64:67]
	v_add_u32_e32 v220, v220, v181
	ds_read_b128 v[212:215], v220
	ds_read_b128 v[216:219], v220 offset:2048
	ds_read_b128 v[230:233], v220 offset:4096
	ds_read_b128 v[234:237], v220 offset:6144
	s_waitcnt lgkmcnt(7)
	v_mfma_f32_16x16x32_bf16 v[60:63], v[196:199], v[238:241], v[60:63]
	v_mfma_f32_16x16x32_bf16 v[56:59], v[200:203], v[238:241], v[56:59]
	v_mfma_f32_16x16x32_bf16 v[52:55], v[204:207], v[238:241], v[52:55]
	v_mfma_f32_16x16x32_bf16 v[48:51], v[208:211], v[238:241], v[48:51]
	s_waitcnt lgkmcnt(6)
	v_mfma_f32_16x16x32_bf16 v[44:47], v[196:199], v[242:245], v[44:47]
	v_mfma_f32_16x16x32_bf16 v[40:43], v[200:203], v[242:245], v[40:43]
	v_mfma_f32_16x16x32_bf16 v[36:39], v[204:207], v[242:245], v[36:39]
	v_mfma_f32_16x16x32_bf16 v[32:35], v[208:211], v[242:245], v[32:35]
	s_waitcnt lgkmcnt(5)
	v_mfma_f32_16x16x32_bf16 v[28:31], v[196:199], v[246:249], v[28:31]
	v_mfma_f32_16x16x32_bf16 v[24:27], v[200:203], v[246:249], v[24:27]
	v_mfma_f32_16x16x32_bf16 v[20:23], v[204:207], v[246:249], v[20:23]
	v_mfma_f32_16x16x32_bf16 v[16:19], v[208:211], v[246:249], v[16:19]
	s_waitcnt lgkmcnt(4)
	v_mfma_f32_16x16x32_bf16 v[12:15], v[196:199], v[250:253], v[12:15]
	v_mfma_f32_16x16x32_bf16 v[8:11], v[200:203], v[250:253], v[8:11]
	v_mfma_f32_16x16x32_bf16 v[4:7], v[204:207], v[250:253], v[4:7]
	v_mfma_f32_16x16x32_bf16 v[0:3], v[208:211], v[250:253], v[0:3]
	v_add_u32_e32 v195, v195, v181
	ds_read_b128 v[196:199], v195 offset:32768
	ds_read_b128 v[200:203], v195 offset:34816
	ds_read_b128 v[204:207], v195 offset:36864
	ds_read_b128 v[208:211], v195 offset:38912
	ds_read_b128 v[238:241], v220 offset:8192
	ds_read_b128 v[242:245], v220 offset:10240
	ds_read_b128 v[246:249], v220 offset:12288
	ds_read_b128 v[250:253], v220 offset:14336
	s_waitcnt lgkmcnt(4)
	v_mfma_f32_16x16x32_bf16 v[124:127], v[196:199], v[212:215], v[124:127]
	v_mfma_f32_16x16x32_bf16 v[120:123], v[200:203], v[212:215], v[120:123]
	v_mfma_f32_16x16x32_bf16 v[116:119], v[204:207], v[212:215], v[116:119]
	v_mfma_f32_16x16x32_bf16 v[112:115], v[208:211], v[212:215], v[112:115]
	v_mfma_f32_16x16x32_bf16 v[108:111], v[196:199], v[216:219], v[108:111]
	v_mfma_f32_16x16x32_bf16 v[104:107], v[200:203], v[216:219], v[104:107]
	v_mfma_f32_16x16x32_bf16 v[100:103], v[204:207], v[216:219], v[100:103]
	v_mfma_f32_16x16x32_bf16 v[96:99], v[208:211], v[216:219], v[96:99]
	v_mfma_f32_16x16x32_bf16 v[92:95], v[196:199], v[230:233], v[92:95]
	v_mfma_f32_16x16x32_bf16 v[88:91], v[200:203], v[230:233], v[88:91]
	v_mfma_f32_16x16x32_bf16 v[84:87], v[204:207], v[230:233], v[84:87]
	v_mfma_f32_16x16x32_bf16 v[80:83], v[208:211], v[230:233], v[80:83]
	v_mfma_f32_16x16x32_bf16 v[76:79], v[196:199], v[234:237], v[76:79]
	v_mfma_f32_16x16x32_bf16 v[72:75], v[200:203], v[234:237], v[72:75]
	v_mfma_f32_16x16x32_bf16 v[68:71], v[204:207], v[234:237], v[68:71]
	v_mfma_f32_16x16x32_bf16 v[64:67], v[208:211], v[234:237], v[64:67]
	s_waitcnt lgkmcnt(0)
	v_mfma_f32_16x16x32_bf16 v[60:63], v[196:199], v[238:241], v[60:63]
	v_mfma_f32_16x16x32_bf16 v[56:59], v[200:203], v[238:241], v[56:59]
	v_mfma_f32_16x16x32_bf16 v[52:55], v[204:207], v[238:241], v[52:55]
	v_mfma_f32_16x16x32_bf16 v[48:51], v[208:211], v[238:241], v[48:51]
	v_mfma_f32_16x16x32_bf16 v[44:47], v[196:199], v[242:245], v[44:47]
	v_mfma_f32_16x16x32_bf16 v[40:43], v[200:203], v[242:245], v[40:43]
	v_mfma_f32_16x16x32_bf16 v[36:39], v[204:207], v[242:245], v[36:39]
	v_mfma_f32_16x16x32_bf16 v[32:35], v[208:211], v[242:245], v[32:35]
	v_mfma_f32_16x16x32_bf16 v[28:31], v[196:199], v[246:249], v[28:31]
	v_mfma_f32_16x16x32_bf16 v[24:27], v[200:203], v[246:249], v[24:27]
	v_mfma_f32_16x16x32_bf16 v[20:23], v[204:207], v[246:249], v[20:23]
	v_mfma_f32_16x16x32_bf16 v[16:19], v[208:211], v[246:249], v[16:19]
	v_mfma_f32_16x16x32_bf16 v[12:15], v[196:199], v[250:253], v[12:15]
	v_mfma_f32_16x16x32_bf16 v[8:11], v[200:203], v[250:253], v[8:11]
	v_mfma_f32_16x16x32_bf16 v[4:7], v[204:207], v[250:253], v[4:7]
	v_mfma_f32_16x16x32_bf16 v[0:3], v[208:211], v[250:253], v[0:3]
	s_add_i32 s42, s42, 0x10000
	s_add_u32 s96, s96, 0x80
	s_addc_u32 s97, s97, 0
	v_add_u32_e32 v195, v185, v180
	v_add_u32_e32 v220, v186, v180
	s_waitcnt vmcnt(0)
	s_waitcnt vmcnt(0)
	s_barrier
	ds_read_b128 v[174:177], v195 offset:6144
	ds_read_b128 v[196:199], v195 offset:4096
	ds_read_b128 v[200:203], v195 offset:2048
	ds_read_b128 v[204:207], v195
	ds_read_b128 v[208:211], v220 offset:6144
	ds_read_b128 v[212:215], v220 offset:4096
	ds_read_b128 v[216:219], v220 offset:2048
	ds_read_b128 v[230:233], v220
	ds_read_b128 v[234:237], v195 offset:8192
	ds_read_b128 v[238:241], v195 offset:10240
	ds_read_b128 v[242:245], v195 offset:12288
	ds_read_b128 v[246:249], v195 offset:14336
	s_waitcnt lgkmcnt(5)
	v_mfma_f32_16x16x32_bf16 v[120:123], v[216:219], v[204:207], v[120:123]
	v_mfma_f32_16x16x32_bf16 v[116:119], v[212:215], v[204:207], v[116:119]
	v_mfma_f32_16x16x32_bf16 v[112:115], v[208:211], v[204:207], v[112:115]
	s_waitcnt lgkmcnt(4)
	v_mfma_f32_16x16x32_bf16 v[108:111], v[230:233], v[200:203], v[108:111]
	v_mfma_f32_16x16x32_bf16 v[104:107], v[216:219], v[200:203], v[104:107]
	v_mfma_f32_16x16x32_bf16 v[96:99], v[208:211], v[200:203], v[96:99]
	v_mfma_f32_16x16x32_bf16 v[92:95], v[230:233], v[196:199], v[92:95]
	v_mfma_f32_16x16x32_bf16 v[84:87], v[212:215], v[196:199], v[84:87]
	v_mfma_f32_16x16x32_bf16 v[76:79], v[230:233], v[174:177], v[76:79]
	v_mfma_f32_16x16x32_bf16 v[72:75], v[216:219], v[174:177], v[72:75]
	v_mfma_f32_16x16x32_bf16 v[124:127], v[230:233], v[204:207], v[124:127]
	v_mfma_f32_16x16x32_bf16 v[100:103], v[212:215], v[200:203], v[100:103]
	v_mfma_f32_16x16x32_bf16 v[88:91], v[216:219], v[196:199], v[88:91]
	v_mfma_f32_16x16x32_bf16 v[80:83], v[208:211], v[196:199], v[80:83]
	v_mfma_f32_16x16x32_bf16 v[68:71], v[212:215], v[174:177], v[68:71]
	v_mfma_f32_16x16x32_bf16 v[64:67], v[208:211], v[174:177], v[64:67]
	v_add_u32_e32 v195, v185, v181
	ds_read_b128 v[174:177], v195
	ds_read_b128 v[196:199], v195 offset:2048
	ds_read_b128 v[200:203], v195 offset:4096
	ds_read_b128 v[204:207], v195 offset:6144
	s_waitcnt lgkmcnt(7)
	v_mfma_f32_16x16x32_bf16 v[60:63], v[230:233], v[234:237], v[60:63]
	v_mfma_f32_16x16x32_bf16 v[56:59], v[216:219], v[234:237], v[56:59]
	v_mfma_f32_16x16x32_bf16 v[52:55], v[212:215], v[234:237], v[52:55]
	v_mfma_f32_16x16x32_bf16 v[48:51], v[208:211], v[234:237], v[48:51]
	s_waitcnt lgkmcnt(6)
	v_mfma_f32_16x16x32_bf16 v[44:47], v[230:233], v[238:241], v[44:47]
	v_mfma_f32_16x16x32_bf16 v[40:43], v[216:219], v[238:241], v[40:43]
	v_mfma_f32_16x16x32_bf16 v[36:39], v[212:215], v[238:241], v[36:39]
	v_mfma_f32_16x16x32_bf16 v[32:35], v[208:211], v[238:241], v[32:35]
	s_waitcnt lgkmcnt(5)
	v_mfma_f32_16x16x32_bf16 v[28:31], v[230:233], v[242:245], v[28:31]
	v_mfma_f32_16x16x32_bf16 v[24:27], v[216:219], v[242:245], v[24:27]
	v_mfma_f32_16x16x32_bf16 v[20:23], v[212:215], v[242:245], v[20:23]
	v_mfma_f32_16x16x32_bf16 v[16:19], v[208:211], v[242:245], v[16:19]
	s_waitcnt lgkmcnt(4)
	v_mfma_f32_16x16x32_bf16 v[12:15], v[230:233], v[246:249], v[12:15]
	v_mfma_f32_16x16x32_bf16 v[8:11], v[216:219], v[246:249], v[8:11]
	v_mfma_f32_16x16x32_bf16 v[4:7], v[212:215], v[246:249], v[4:7]
	v_mfma_f32_16x16x32_bf16 v[0:3], v[208:211], v[246:249], v[0:3]
	v_add_u32_e32 v220, v186, v181
	ds_read_b128 v[208:211], v220
	ds_read_b128 v[212:215], v220 offset:2048
	ds_read_b128 v[216:219], v220 offset:4096
	ds_read_b128 v[230:233], v220 offset:6144
	ds_read_b128 v[234:237], v195 offset:8192
	ds_read_b128 v[238:241], v195 offset:10240
	ds_read_b128 v[242:245], v195 offset:12288
	ds_read_b128 v[246:249], v195 offset:14336
	s_waitcnt lgkmcnt(6)
	v_mfma_f32_16x16x32_bf16 v[120:123], v[212:215], v[174:177], v[120:123]
	s_waitcnt lgkmcnt(5)
	v_mfma_f32_16x16x32_bf16 v[116:119], v[216:219], v[174:177], v[116:119]
	s_waitcnt lgkmcnt(4)
	v_mfma_f32_16x16x32_bf16 v[112:115], v[230:233], v[174:177], v[112:115]
	v_mfma_f32_16x16x32_bf16 v[108:111], v[208:211], v[196:199], v[108:111]
	v_mfma_f32_16x16x32_bf16 v[104:107], v[212:215], v[196:199], v[104:107]
	v_mfma_f32_16x16x32_bf16 v[96:99], v[230:233], v[196:199], v[96:99]
	v_mfma_f32_16x16x32_bf16 v[92:95], v[208:211], v[200:203], v[92:95]
	v_mfma_f32_16x16x32_bf16 v[84:87], v[216:219], v[200:203], v[84:87]
	v_mfma_f32_16x16x32_bf16 v[76:79], v[208:211], v[204:207], v[76:79]
	v_mfma_f32_16x16x32_bf16 v[72:75], v[212:215], v[204:207], v[72:75]
	v_mfma_f32_16x16x32_bf16 v[124:127], v[208:211], v[174:177], v[124:127]
	v_mfma_f32_16x16x32_bf16 v[100:103], v[216:219], v[196:199], v[100:103]
	v_mfma_f32_16x16x32_bf16 v[88:91], v[212:215], v[200:203], v[88:91]
	v_mfma_f32_16x16x32_bf16 v[80:83], v[230:233], v[200:203], v[80:83]
	v_mfma_f32_16x16x32_bf16 v[68:71], v[216:219], v[204:207], v[68:71]
	v_mfma_f32_16x16x32_bf16 v[64:67], v[230:233], v[204:207], v[64:67]
	s_waitcnt lgkmcnt(3)
	v_mfma_f32_16x16x32_bf16 v[60:63], v[208:211], v[234:237], v[60:63]
	v_mfma_f32_16x16x32_bf16 v[56:59], v[212:215], v[234:237], v[56:59]
	v_mfma_f32_16x16x32_bf16 v[52:55], v[216:219], v[234:237], v[52:55]
	v_mfma_f32_16x16x32_bf16 v[48:51], v[230:233], v[234:237], v[48:51]
	s_waitcnt lgkmcnt(2)
	v_mfma_f32_16x16x32_bf16 v[44:47], v[208:211], v[238:241], v[44:47]
	v_mfma_f32_16x16x32_bf16 v[40:43], v[212:215], v[238:241], v[40:43]
	v_mfma_f32_16x16x32_bf16 v[36:39], v[216:219], v[238:241], v[36:39]
	v_mfma_f32_16x16x32_bf16 v[32:35], v[230:233], v[238:241], v[32:35]
	s_waitcnt lgkmcnt(1)
	v_mfma_f32_16x16x32_bf16 v[28:31], v[208:211], v[242:245], v[28:31]
	v_mfma_f32_16x16x32_bf16 v[24:27], v[212:215], v[242:245], v[24:27]
	v_mfma_f32_16x16x32_bf16 v[20:23], v[216:219], v[242:245], v[20:23]
	v_mfma_f32_16x16x32_bf16 v[16:19], v[230:233], v[242:245], v[16:19]
	s_waitcnt lgkmcnt(0)
	v_mfma_f32_16x16x32_bf16 v[12:15], v[208:211], v[246:249], v[12:15]
	v_mfma_f32_16x16x32_bf16 v[8:11], v[212:215], v[246:249], v[8:11]
	v_mfma_f32_16x16x32_bf16 v[4:7], v[216:219], v[246:249], v[4:7]
	v_mfma_f32_16x16x32_bf16 v[0:3], v[230:233], v[246:249], v[0:3]
	v_mov_b64_e32 v[174:175], v[138:139]
	s_barrier
	v_cvt_pk_bf16_f32 v124, v124, v125
	v_lshl_add_u32 v174, v174, 1, 0
	v_cvt_pk_bf16_f32 v125, v126, v127
	v_cvt_pk_bf16_f32 v120, v120, v121
	v_cvt_pk_bf16_f32 v121, v122, v123
	v_cvt_pk_bf16_f32 v116, v116, v117
	v_cvt_pk_bf16_f32 v117, v118, v119
	v_cvt_pk_bf16_f32 v112, v112, v113
	v_cvt_pk_bf16_f32 v113, v114, v115
	ds_write2_b64 v174, v[124:125], v[120:121] offset1:4
	ds_write2_b64 v174, v[116:117], v[112:113] offset0:32 offset1:36
	v_mov_b64_e32 v[112:113], v[140:141]
	v_cvt_pk_bf16_f32 v108, v108, v109
	v_lshl_add_u32 v112, v112, 1, 0
	v_cvt_pk_bf16_f32 v109, v110, v111
	v_cvt_pk_bf16_f32 v104, v104, v105
	v_cvt_pk_bf16_f32 v105, v106, v107
	v_cvt_pk_bf16_f32 v100, v100, v101
	v_cvt_pk_bf16_f32 v101, v102, v103
	v_cvt_pk_bf16_f32 v96, v96, v97
	v_cvt_pk_bf16_f32 v97, v98, v99
	ds_write2_b64 v112, v[108:109], v[104:105] offset1:4
	ds_write2_b64 v112, v[100:101], v[96:97] offset0:32 offset1:36
	v_mov_b64_e32 v[96:97], v[142:143]
	v_cvt_pk_bf16_f32 v92, v92, v93
	v_lshl_add_u32 v96, v96, 1, 0
	v_cvt_pk_bf16_f32 v93, v94, v95
	v_cvt_pk_bf16_f32 v88, v88, v89
	v_cvt_pk_bf16_f32 v89, v90, v91
	v_cvt_pk_bf16_f32 v84, v84, v85
	v_cvt_pk_bf16_f32 v85, v86, v87
	v_cvt_pk_bf16_f32 v80, v80, v81
	v_cvt_pk_bf16_f32 v81, v82, v83
	ds_write2_b64 v96, v[92:93], v[88:89] offset1:4
	ds_write2_b64 v96, v[84:85], v[80:81] offset0:32 offset1:36
	v_mov_b64_e32 v[80:81], v[144:145]
	v_cvt_pk_bf16_f32 v76, v76, v77
	v_lshl_add_u32 v80, v80, 1, 0
	v_cvt_pk_bf16_f32 v77, v78, v79
	v_cvt_pk_bf16_f32 v72, v72, v73
	v_cvt_pk_bf16_f32 v73, v74, v75
	v_cvt_pk_bf16_f32 v68, v68, v69
	v_cvt_pk_bf16_f32 v69, v70, v71
	v_cvt_pk_bf16_f32 v64, v64, v65
	v_cvt_pk_bf16_f32 v65, v66, v67
	ds_write2_b64 v80, v[76:77], v[72:73] offset1:4
	ds_write2_b64 v80, v[68:69], v[64:65] offset0:32 offset1:36
	v_mov_b64_e32 v[64:65], v[146:147]
	v_cvt_pk_bf16_f32 v60, v60, v61
	v_lshl_add_u32 v64, v64, 1, 0
	v_cvt_pk_bf16_f32 v61, v62, v63
	v_cvt_pk_bf16_f32 v56, v56, v57
	v_cvt_pk_bf16_f32 v57, v58, v59
	v_cvt_pk_bf16_f32 v52, v52, v53
	v_cvt_pk_bf16_f32 v53, v54, v55
	v_cvt_pk_bf16_f32 v48, v48, v49
	v_cvt_pk_bf16_f32 v49, v50, v51
	ds_write2_b64 v64, v[60:61], v[56:57] offset1:4
	ds_write2_b64 v64, v[52:53], v[48:49] offset0:32 offset1:36
	v_mov_b64_e32 v[48:49], v[148:149]
	v_cvt_pk_bf16_f32 v44, v44, v45
	v_lshl_add_u32 v48, v48, 1, 0
	v_cvt_pk_bf16_f32 v45, v46, v47
	v_cvt_pk_bf16_f32 v40, v40, v41
	v_cvt_pk_bf16_f32 v41, v42, v43
	v_cvt_pk_bf16_f32 v36, v36, v37
	v_cvt_pk_bf16_f32 v37, v38, v39
	v_cvt_pk_bf16_f32 v32, v32, v33
	v_cvt_pk_bf16_f32 v33, v34, v35
	ds_write2_b64 v48, v[44:45], v[40:41] offset1:4
	ds_write2_b64 v48, v[36:37], v[32:33] offset0:32 offset1:36
	v_mov_b64_e32 v[32:33], v[150:151]
	v_cvt_pk_bf16_f32 v28, v28, v29
	v_lshl_add_u32 v32, v32, 1, 0
	v_cvt_pk_bf16_f32 v29, v30, v31
	v_cvt_pk_bf16_f32 v24, v24, v25
	v_cvt_pk_bf16_f32 v25, v26, v27
	v_cvt_pk_bf16_f32 v20, v20, v21
	v_cvt_pk_bf16_f32 v21, v22, v23
	v_cvt_pk_bf16_f32 v16, v16, v17
	v_cvt_pk_bf16_f32 v17, v18, v19
	ds_write2_b64 v32, v[28:29], v[24:25] offset1:4
	ds_write2_b64 v32, v[20:21], v[16:17] offset0:32 offset1:36
	v_mov_b64_e32 v[16:17], v[152:153]
	v_cvt_pk_bf16_f32 v12, v12, v13
	v_lshl_add_u32 v16, v16, 1, 0
	v_cvt_pk_bf16_f32 v13, v14, v15
	v_cvt_pk_bf16_f32 v8, v8, v9
	v_cvt_pk_bf16_f32 v9, v10, v11
	v_cvt_pk_bf16_f32 v4, v4, v5
	v_cvt_pk_bf16_f32 v5, v6, v7
	v_cvt_pk_bf16_f32 v0, v0, v1
	v_cvt_pk_bf16_f32 v1, v2, v3
	ds_write2_b64 v16, v[12:13], v[8:9] offset1:4
	ds_write2_b64 v16, v[4:5], v[0:1] offset0:32 offset1:36
	v_lshl_or_b32 v72, s58, 7, v182
	v_mov_b64_e32 v[0:1], s[54:55]
	v_mov_b64_e32 v[2:3], s[56:57]
	v_mov_b64_e32 v[120:121], s[50:51]
	v_mov_b64_e32 v[74:75], s[52:53]
	v_ashrrev_i32_e32 v73, 31, v72
	v_lshlrev_b64 v[4:5], 2, v[72:73]
	v_lshl_add_u64 v[0:1], v[0:1], 0, v[4:5]
	s_mov_b64 s[42:43], 0x5800
	v_lshl_add_u64 v[8:9], v[0:1], 0, s[42:43]
	s_mov_b64 s[42:43], 0x8400
	v_lshl_add_u64 v[10:11], v[0:1], 0, s[42:43]
	s_mov_b64 s[42:43], 0xb000
	v_lshl_add_u64 v[20:21], v[0:1], 0, s[42:43]
	s_mov_b64 s[42:43], 0xdc00
	v_lshl_add_u64 v[30:31], v[2:3], 0, v[4:5]
	v_add_co_u32_e32 v2, vcc, s3, v0
	v_lshl_add_u64 v[28:29], v[0:1], 0, s[42:43]
	s_nop 0
	v_addc_co_u32_e32 v3, vcc, 0, v1, vcc
	s_movk_i32 s42, 0x5000
	v_add_co_u32_e32 v4, vcc, s42, v0
	s_mov_b32 s42, 0xb000
	s_nop 0
	v_addc_co_u32_e32 v5, vcc, 0, v1, vcc
	flat_load_dwordx4 v[32:35], v[2:3] offset:3072
	flat_load_dwordx4 v[44:47], v[4:5] offset:2048
	v_add_co_u32_e32 v2, vcc, s66, v0
	s_mov_b64 s[48:49], 0x2c00
	s_nop 0
	v_addc_co_u32_e32 v3, vcc, 0, v1, vcc
	v_add_co_u32_e32 v4, vcc, s42, v0
	v_lshl_add_u64 v[6:7], v[0:1], 0, s[48:49]
	s_nop 0
	v_addc_co_u32_e32 v5, vcc, 0, v1, vcc
	flat_load_dwordx4 v[36:39], v[2:3] offset:1024
	flat_load_dwordx4 v[52:55], v[4:5]
	v_add_co_u32_e32 v2, vcc, s87, v0
	v_lshl_add_u64 v[64:65], v[30:31], 0, s[48:49]
	s_nop 0
	v_addc_co_u32_e32 v3, vcc, 0, v1, vcc
	flat_load_dwordx4 v[40:43], v[2:3] offset:3072
	v_add_co_u32_e32 v2, vcc, s3, v30
	v_mov_b32_e32 v76, 0
	s_nop 0
	v_addc_co_u32_e32 v3, vcc, 0, v31, vcc
	flat_load_dwordx4 v[48:51], v[2:3] offset:3072
	flat_load_dwordx4 v[56:59], v[0:1]
	flat_load_dwordx4 v[16:19], v[0:1] offset:16
	s_nop 0
	flat_load_dwordx4 v[0:3], v[6:7] offset:16
	flat_load_dwordx4 v[24:27], v[8:9] offset:16
	flat_load_dwordx4 v[12:15], v[10:11] offset:16
	s_nop 0
	flat_load_dwordx4 v[20:23], v[20:21] offset:16
	s_nop 0
	flat_load_dwordx4 v[4:7], v[28:29] offset:16
	flat_load_dwordx4 v[60:63], v[30:31]
	s_nop 0
	flat_load_dwordx4 v[28:31], v[30:31] offset:16
	s_nop 0
	flat_load_dwordx4 v[8:11], v[64:65] offset:16
	v_mov_b32_e32 v94, 0
	v_mov_b32_e32 v95, 0
	v_mov_b32_e32 v86, 0
	v_mov_b32_e32 v87, 0
	v_mov_b32_e32 v106, 0
	v_mov_b32_e32 v107, 0
	v_mov_b32_e32 v98, 0
	v_mov_b32_e32 v99, 0
	v_mov_b32_e32 v114, 0
	v_mov_b32_e32 v115, 0
	v_mov_b32_e32 v110, 0
	v_mov_b32_e32 v111, 0
	v_mov_b32_e32 v118, 0
	v_mov_b32_e32 v119, 0
	v_mov_b32_e32 v116, 0
	v_mov_b32_e32 v117, 0
	s_waitcnt lgkmcnt(0)
	s_barrier
	s_and_saveexec_b64 s[58:59], s[4:5]
	s_cbranch_execz .LBB0_834
	ds_read_b128 v[64:67], v137
	ds_read_b128 v[68:71], v184
	s_waitcnt lgkmcnt(0)
	v_lshlrev_b32_e32 v118, 16, v64
	v_and_b32_e32 v119, 0xffff0000, v64
	v_lshlrev_b32_e32 v116, 16, v68
	v_and_b32_e32 v117, 0xffff0000, v68
	v_lshlrev_b32_e32 v114, 16, v65
	v_and_b32_e32 v115, 0xffff0000, v65
	v_lshlrev_b32_e32 v110, 16, v69
	v_and_b32_e32 v111, 0xffff0000, v69
	v_lshlrev_b32_e32 v106, 16, v66
	v_and_b32_e32 v107, 0xffff0000, v66
	v_lshlrev_b32_e32 v98, 16, v70
	v_and_b32_e32 v99, 0xffff0000, v70
	v_lshlrev_b32_e32 v94, 16, v67
	v_and_b32_e32 v95, 0xffff0000, v67
	v_lshlrev_b32_e32 v86, 16, v71
	v_and_b32_e32 v87, 0xffff0000, v71
